# norm1/norm2 phases: 30 of the 35 gain/scale/shift vector loads per row pair issued before one wait (was a 14-step load-wait-compute-store ladder)
# speedup vs baseline: 1.0041x; 1.0018x over previous
; __device__ __forceinline__ void norm_rows(const float* xl, const float* xc, const float* g, const float* modl, int sh_ofs, int sc_ofs, bf16_t* XN, int nrows, int gw, int NGW) {
;     ...
;     for (int row = gw; row < nrows; row += 2 * NGW) {
;         const int rowb = (row + NGW < nrows) ? row + NGW : row;
;         const f32x4* s4a = (const f32x4*)(row < RL ? xl + (size_t)row * DM : xc + (size_t)(row - RL) * DM) + lane;
;         const f32x4* s4b = (const f32x4*)(rowb < RL ? xl + (size_t)rowb * DM : xc + (size_t)(rowb - RL) * DM) + lane;
;         const int mia = row < RL ? (row >> 11) : 16, mib = rowb < RL ? (rowb >> 11) : 16;
;         f32x4 va[8], vb[8]; float ssa = 0.f, ssb = 0.f;
; #pragma unroll
;         for (int j = 0; j < 8; ++j) { va[j] = __builtin_nontemporal_load(s4a + 64 * j); vb[j] = __builtin_nontemporal_load(s4b + 64 * j); }
; #pragma unroll
;         for (int j = 0; j < 8; ++j) { ssa += (va[j][0] * va[j][0] + va[j][1] * va[j][1]) + (va[j][2] * va[j][2] + va[j][3] * va[j][3]); ssb += (vb[j][0] * vb[j][0] + vb[j][1] * vb[j][1]) + (vb[j][2] * vb[j][2] + vb[j][3] * vb[j][3]); }
;         const float rsa = rsqrtf(wave_sum(ssa) * (1.0f / DM) + EPS), rsb = rsqrtf(wave_sum(ssb) * (1.0f / DM) + EPS);
;         const f32x4* g4 = (const f32x4*)g + lane;
;         const f32x4* sca = (const f32x4*)(modl + (size_t)mia * 12288 + sc_ofs) + lane; const f32x4* sha = (const f32x4*)(modl + (size_t)mia * 12288 + sh_ofs) + lane;
;         const f32x4* scb = (const f32x4*)(modl + (size_t)mib * 12288 + sc_ofs) + lane; const f32x4* shb = (const f32x4*)(modl + (size_t)mib * 12288 + sh_ofs) + lane;
;         u32x2* oa = (u32x2*)(XN + (size_t)row * DM) + lane; u32x2* ob = (u32x2*)(XN + (size_t)rowb * DM) + lane;
.LBB0_156:
	s_add_i32 s18, s46, 0xffff8000
	v_readlane_b32 s44, v255, 1
	v_readlane_b32 s45, v255, 2
	s_add_u32 s44, s44, s30
	s_addc_u32 s45, s45, s31
	s_cmp_lt_i32 s46, 0x8000
	global_load_dwordx4 v[56:59], v208, s[42:43] nt
	global_load_dwordx4 v[44:47], v208, s[42:43] offset:1024 nt
	global_load_dwordx4 v[40:43], v208, s[42:43] offset:2048 nt
	s_cselect_b32 s45, s45, 0
	s_cselect_b32 s44, s44, s18
	v_lshl_add_u64 v[0:1], s[42:43], 0, v[208:209]
	s_cselect_b32 s18, s17, s41
	s_cselect_b32 s47, s16, s40
	s_lshl_b64 s[44:45], s[44:45], 13
	v_add_co_u32_e32 v0, vcc, s96, v0
	s_add_u32 s44, s47, s44
	s_nop 0
	v_addc_co_u32_e32 v1, vcc, 0, v1, vcc
	s_addc_u32 s45, s18, s45
	global_load_dwordx4 v[24:27], v[0:1], off nt
	global_load_dwordx4 v[60:63], v208, s[44:45] nt
	global_load_dwordx4 v[52:55], v208, s[44:45] offset:1024 nt
	global_load_dwordx4 v[48:51], v208, s[44:45] offset:2048 nt
	global_load_dwordx4 v[36:39], v208, s[44:45] offset:3072 nt
	v_lshl_add_u64 v[2:3], s[44:45], 0, v[208:209]
	v_add_co_u32_e32 v4, vcc, s96, v2
	s_min_i32 s18, s46, 0x8000
	s_nop 0
	v_addc_co_u32_e32 v5, vcc, 0, v3, vcc
	global_load_dwordx4 v[28:31], v[4:5], off nt
	global_load_dwordx4 v[32:35], v208, s[42:43] offset:3072 nt
	global_load_dwordx4 v[20:23], v[4:5], off offset:1024 nt
	global_load_dwordx4 v[16:19], v[0:1], off offset:1024 nt
	global_load_dwordx4 v[8:11], v[0:1], off offset:2048 nt
	s_nop 0
	global_load_dwordx4 v[0:3], v[0:1], off offset:3072 nt
	s_nop 0
	global_load_dwordx4 v[12:15], v[4:5], off offset:2048 nt
	s_nop 0
	global_load_dwordx4 v[4:7], v[4:5], off offset:3072 nt
	s_min_i32 s42, s34, 0x8000
	s_ashr_i32 s18, s18, 11
	s_ashr_i32 s44, s42, 11
	s_mul_hi_i32 s43, s18, 0xc000
	s_mul_i32 s18, s18, 0xc000
	v_readlane_b32 s49, v255, 3
	s_add_u32 s42, s49, s18
	v_readlane_b32 s50, v255, 4
	s_addc_u32 s43, s50, s43
	v_lshl_add_u64 v[108:109], s[42:43], 0, v[208:209]
	s_mov_b32 s47, 0x9000
	s_movk_i32 s48, 0x7000
	s_mov_b32 s2, 0x3a000000
	s_mov_b32 s45, 0x800000
	s_mul_hi_i32 s18, s44, 0xc000
	s_mul_i32 s44, s44, 0xc000
	s_add_u32 s42, s49, s44
	s_addc_u32 s43, s50, s18
	s_lshl_b64 s[34:35], s[34:35], 12
	s_add_i32 s46, s46, s78
	s_add_u32 s30, s30, s78
	s_addc_u32 s31, s31, s79
	s_cmp_lt_i32 s46, s29
	s_waitcnt vmcnt(0)
	v_mov_b32_e32 v80, v57
	v_mov_b32_e32 v81, v45
	v_mov_b32_e32 v86, v59
	v_mov_b32_e32 v87, v47
	v_pk_mul_f32 v[94:95], v[42:43], v[42:43]
	v_pk_mul_f32 v[96:97], v[40:41], v[40:41]
	v_mov_b32_e32 v78, v56
	v_mov_b32_e32 v79, v44
	v_mov_b32_e32 v84, v58
	v_mov_b32_e32 v85, v46
	v_pk_mul_f32 v[80:81], v[80:81], v[80:81]
	v_pk_mul_f32 v[86:87], v[86:87], v[86:87]
	v_pk_mov_b32 v[98:99], v[96:97], v[94:95] op_sel:[1,0]
	v_mov_b32_e32 v97, v95
	v_pk_fma_f32 v[78:79], v[78:79], v[78:79], v[80:81]
	v_pk_fma_f32 v[80:81], v[84:85], v[84:85], v[86:87]
	v_pk_add_f32 v[84:85], v[98:99], v[96:97]
	v_mov_b32_e32 v86, v61
	v_mov_b32_e32 v87, v53
	v_mov_b32_e32 v96, v63
	v_mov_b32_e32 v97, v55
	v_pk_add_f32 v[78:79], v[78:79], v[80:81]
	v_mov_b32_e32 v80, v60
	v_mov_b32_e32 v81, v52
	v_mov_b32_e32 v94, v62
	v_mov_b32_e32 v95, v54
	v_pk_mul_f32 v[98:99], v[50:51], v[50:51]
	v_pk_mul_f32 v[100:101], v[48:49], v[48:49]
	v_pk_mul_f32 v[86:87], v[86:87], v[86:87]
	v_pk_mul_f32 v[96:97], v[96:97], v[96:97]
	v_pk_mov_b32 v[104:105], v[100:101], v[98:99] op_sel:[1,0]
	v_mov_b32_e32 v101, v99
	v_pk_fma_f32 v[80:81], v[80:81], v[80:81], v[86:87]
	v_pk_fma_f32 v[86:87], v[94:95], v[94:95], v[96:97]
	v_mul_f32_e32 v82, v37, v37
	v_mul_f32_e32 v102, v39, v39
	v_pk_add_f32 v[94:95], v[104:105], v[100:101]
	v_pk_add_f32 v[80:81], v[80:81], v[86:87]
	v_mul_f32_e32 v93, v24, v24
	v_mul_f32_e32 v106, v25, v25
	v_pk_fma_f32 v[98:99], v[36:37], v[36:37], v[82:83] op_sel_hi:[1,1,0]
	v_pk_fma_f32 v[102:103], v[38:39], v[38:39], v[102:103] op_sel_hi:[1,1,0]
	v_mul_f32_e32 v82, v28, v28
	v_mul_f32_e32 v96, v29, v29
	v_pk_add_f32 v[86:87], v[94:95], v[94:95] op_sel:[0,1] op_sel_hi:[1,0]
	v_pk_add_f32 v[80:81], v[80:81], v[80:81] op_sel:[0,1] op_sel_hi:[1,0]
	v_pk_add_f32 v[78:79], v[78:79], v[78:79] op_sel:[0,1] op_sel_hi:[1,0]
	v_pk_add_f32 v[84:85], v[84:85], v[84:85] op_sel:[0,1] op_sel_hi:[1,0]
	v_mul_f32_e32 v99, v30, v30
	v_mul_f32_e32 v103, v31, v31
	v_mov_b32_e32 v87, v96
	v_mov_b32_e32 v81, v82
	v_mov_b32_e32 v79, v93
	v_mov_b32_e32 v85, v106
	v_mul_f32_e32 v82, v33, v33
	v_pk_add_f32 v[94:95], v[98:99], v[102:103]
	v_pk_add_f32 v[80:81], v[80:81], v[86:87]
	v_pk_add_f32 v[78:79], v[78:79], v[84:85]
	v_pk_fma_f32 v[84:85], v[32:33], v[32:33], v[82:83] op_sel_hi:[1,1,0]
	v_mul_f32_e32 v82, v35, v35
	v_mul_f32_e32 v107, v26, v26
	v_pk_add_f32 v[80:81], v[80:81], v[94:95]
	v_mul_f32_e32 v94, v27, v27
	v_pk_fma_f32 v[86:87], v[34:35], v[34:35], v[82:83] op_sel_hi:[1,1,0]
	v_mov_b32_e32 v85, v107
	v_mov_b32_e32 v87, v94
	v_pk_add_f32 v[84:85], v[84:85], v[86:87]
	v_pk_mul_f32 v[86:87], v[20:21], v[20:21]
	v_pk_add_f32 v[78:79], v[78:79], v[84:85]
	v_pk_mul_f32 v[84:85], v[22:23], v[22:23]
	v_mul_f32_e32 v82, v4, v4
	v_pk_mov_b32 v[94:95], v[86:87], v[84:85] op_sel:[1,0]
	v_mov_b32_e32 v87, v85
	v_pk_add_f32 v[84:85], v[94:95], v[86:87]
	v_pk_mul_f32 v[86:87], v[18:19], v[18:19]
	v_pk_mul_f32 v[94:95], v[16:17], v[16:17]
	v_pk_add_f32 v[80:81], v[80:81], v[80:81] op_sel:[0,1] op_sel_hi:[1,0]
	v_pk_mov_b32 v[96:97], v[94:95], v[86:87] op_sel:[1,0]
	v_mul_f32_e32 v86, v5, v5
	v_pk_add_f32 v[84:85], v[84:85], v[84:85] op_sel:[0,1] op_sel_hi:[1,0]
	v_mov_b32_e32 v81, v82
	v_mov_b32_e32 v85, v86
	v_mul_f32_e32 v82, v13, v13
	v_mov_b32_e32 v95, v87
	v_mul_f32_e32 v87, v6, v6
	v_pk_add_f32 v[80:81], v[80:81], v[84:85]
	v_pk_fma_f32 v[84:85], v[12:13], v[12:13], v[82:83] op_sel_hi:[1,1,0]
	v_mul_f32_e32 v82, v15, v15
	v_mul_f32_e32 v93, v7, v7
	v_mov_b32_e32 v85, v87
	v_pk_fma_f32 v[86:87], v[14:15], v[14:15], v[82:83] op_sel_hi:[1,1,0]
	v_pk_add_f32 v[106:107], v[78:79], v[78:79] op_sel:[0,1] op_sel_hi:[1,0]
	v_mov_b32_e32 v87, v93
	v_add_co_u32_e32 v78, vcc, s47, v108
	v_pk_add_f32 v[84:85], v[84:85], v[86:87]
	s_nop 0
	v_addc_co_u32_e32 v79, vcc, 0, v109, vcc
	v_pk_add_f32 v[104:105], v[80:81], v[84:85]
	v_add_co_u32_e32 v80, vcc, s48, v108
	v_pk_add_f32 v[102:103], v[96:97], v[94:95]
	global_load_dwordx4 v[94:97], v[64:65], off
	global_load_dwordx4 v[84:87], v[78:79], off offset:-4096
	v_addc_co_u32_e32 v81, vcc, 0, v109, vcc
	global_load_dwordx4 v[98:101], v[80:81], off offset:-4096
	v_mul_f32_e32 v82, v0, v0
	v_mul_f32_e32 v93, v1, v1
	v_pk_add_f32 v[102:103], v[102:103], v[102:103] op_sel:[0,1] op_sel_hi:[1,0]
	v_mov_b32_e32 v107, v82
	v_mov_b32_e32 v103, v93
	v_mul_f32_e32 v82, v9, v9
	v_mul_f32_e32 v110, v2, v2
	v_pk_add_f32 v[102:103], v[106:107], v[102:103]
	v_pk_fma_f32 v[106:107], v[8:9], v[8:9], v[82:83] op_sel_hi:[1,1,0]
	v_mul_f32_e32 v82, v11, v11
	v_mul_f32_e32 v112, v3, v3
	v_mov_b32_e32 v107, v110
	v_pk_fma_f32 v[110:111], v[10:11], v[10:11], v[82:83] op_sel_hi:[1,1,0]
	s_waitcnt vmcnt(1)
; __device__ __forceinline__ unsigned cvt_pk_bf16(float lo, float hi) { unsigned r; asm volatile("v_cvt_pk_bf16_f32 %0, %1, %2" : "=v"(r) : "v"(lo), "v"(hi)); return r; }
; __device__ __forceinline__ void norm_rows(const float* xl, const float* xc, const float* g, const float* modl, int sh_ofs, int sc_ofs, bf16_t* XN, int nrows, int gw, int NGW) {
;     ...
;         const float rsa = rsqrtf(wave_sum(ssa) * (1.0f / DM) + EPS), rsb = rsqrtf(wave_sum(ssb) * (1.0f / DM) + EPS);
;         const f32x4* g4 = (const f32x4*)g + lane;
;         const f32x4* sca = (const f32x4*)(modl + (size_t)mia * 12288 + sc_ofs) + lane; const f32x4* sha = (const f32x4*)(modl + (size_t)mia * 12288 + sh_ofs) + lane;
;         const f32x4* scb = (const f32x4*)(modl + (size_t)mib * 12288 + sc_ofs) + lane; const f32x4* shb = (const f32x4*)(modl + (size_t)mib * 12288 + sh_ofs) + lane;
;         u32x2* oa = (u32x2*)(XN + (size_t)row * DM) + lane; u32x2* ob = (u32x2*)(XN + (size_t)rowb * DM) + lane;
; #pragma unroll
;         for (int j = 0; j < 8; ++j) { const f32x4 gj = g4[64 * j];
;             const f32x4 ya = va[j] * rsa * gj * (sca[64 * j] + 1.0f) + sha[64 * j]; u32x2 w; w.x = cvt_pk_bf16(ya[0], ya[1]); w.y = cvt_pk_bf16(ya[2], ya[3]); oa[64 * j] = w;
;             const f32x4 yb = vb[j] * rsb * gj * (scb[64 * j] + 1.0f) + shb[64 * j]; u32x2 w2; w2.x = cvt_pk_bf16(yb[0], yb[1]); w2.y = cvt_pk_bf16(yb[2], yb[3]); ob[64 * j] = w2; }
	v_pk_add_f32 v[84:85], v[84:85], 1.0 op_sel_hi:[1,0]
	v_mov_b32_e32 v111, v112
	v_pk_add_f32 v[106:107], v[106:107], v[110:111]
	v_lshl_add_u64 v[110:111], s[42:43], 0, v[208:209]
	v_pk_add_f32 v[102:103], v[102:103], v[106:107]
	v_mov_b32_e32 v107, v104
	v_mov_b32_e32 v106, v102
	v_mov_b32_e32 v104, v103
	v_pk_add_f32 v[102:103], v[106:107], v[104:105]
	ds_bpermute_b32 v105, v83, v103
	ds_bpermute_b32 v104, v83, v102
	v_pk_add_f32 v[86:87], v[86:87], 1.0 op_sel_hi:[1,0]
	s_mov_b64 s[42:43], 0x6000
	s_waitcnt lgkmcnt(0)
	v_pk_add_f32 v[102:103], v[102:103], v[104:105]
	ds_bpermute_b32 v105, v88, v103
	ds_bpermute_b32 v104, v88, v102
	s_waitcnt lgkmcnt(0)
	v_pk_add_f32 v[102:103], v[102:103], v[104:105]
	ds_bpermute_b32 v105, v89, v103
	ds_bpermute_b32 v104, v89, v102
	s_waitcnt lgkmcnt(0)
	v_pk_add_f32 v[102:103], v[102:103], v[104:105]
	ds_bpermute_b32 v105, v90, v103
	ds_bpermute_b32 v104, v90, v102
	s_waitcnt lgkmcnt(0)
	v_pk_add_f32 v[102:103], v[102:103], v[104:105]
	ds_bpermute_b32 v105, v91, v103
	ds_bpermute_b32 v104, v91, v102
	s_waitcnt lgkmcnt(0)
	v_pk_add_f32 v[102:103], v[102:103], v[104:105]
	ds_bpermute_b32 v105, v92, v103
	ds_bpermute_b32 v104, v92, v102
	s_waitcnt lgkmcnt(0)
	v_pk_add_f32 v[102:103], v[102:103], v[104:105]
	s_nop 0
	v_pk_fma_f32 v[106:107], v[102:103], s[2:3], v[238:239] op_sel_hi:[1,0,0]
	s_nop 0
	v_mul_f32_e32 v82, 0x4b800000, v107
	v_cmp_gt_f32_e32 vcc, s45, v107
	s_nop 1
	v_cndmask_b32_e32 v82, v107, v82, vcc
	v_rsq_f32_e32 v82, v82
	s_nop 0
	v_mul_f32_e32 v93, 0x45800000, v82
	v_cndmask_b32_e32 v82, v82, v93, vcc
	v_pk_mul_f32 v[60:61], v[60:61], v[82:83] op_sel_hi:[1,0]
	v_pk_mul_f32 v[62:63], v[62:63], v[82:83] op_sel_hi:[1,0]
	v_pk_mul_f32 v[60:61], v[94:95], v[60:61]
	v_pk_mul_f32 v[62:63], v[96:97], v[62:63]
	s_waitcnt vmcnt(0)
	v_pk_fma_f32 v[60:61], v[84:85], v[60:61], v[98:99]
	v_add_co_u32_e32 v84, vcc, s47, v110
	v_pk_fma_f32 v[62:63], v[86:87], v[62:63], v[100:101]
	s_nop 0
	v_addc_co_u32_e32 v85, vcc, 0, v111, vcc
	v_cvt_pk_bf16_f32 v60, v60, v61
	v_cvt_pk_bf16_f32 v61, v62, v63
	global_store_dwordx2 v[76:77], v[60:61], off
	v_add_co_u32_e32 v86, vcc, s48, v110
	global_load_dwordx4 v[98:101], v[84:85], off offset:-4096
	s_nop 0
	v_addc_co_u32_e32 v87, vcc, 0, v111, vcc
	global_load_dwordx4 v[102:105], v[86:87], off offset:-4096
	v_mul_f32_e32 v60, 0x4b800000, v106
	v_cmp_gt_f32_e32 vcc, s45, v106
	v_pk_mul_f32 v[52:53], v[52:53], v[82:83] op_sel_hi:[1,0]
	v_pk_mul_f32 v[54:55], v[54:55], v[82:83] op_sel_hi:[1,0]
	v_cndmask_b32_e32 v60, v106, v60, vcc
	v_rsq_f32_e32 v60, v60
	v_pk_mul_f32 v[48:49], v[48:49], v[82:83] op_sel_hi:[1,0]
	v_pk_mul_f32 v[50:51], v[50:51], v[82:83] op_sel_hi:[1,0]
	v_pk_mul_f32 v[36:37], v[36:37], v[82:83] op_sel_hi:[1,0]
	v_mul_f32_e32 v61, 0x45800000, v60
	v_cndmask_b32_e32 v62, v60, v61, vcc
	v_pk_mul_f32 v[58:59], v[58:59], v[62:63] op_sel_hi:[1,0]
	v_pk_mul_f32 v[56:57], v[56:57], v[62:63] op_sel_hi:[1,0]
	v_pk_mul_f32 v[58:59], v[96:97], v[58:59]
	v_pk_mul_f32 v[56:57], v[94:95], v[56:57]
	v_lshl_add_u64 v[60:61], v[66:67], 0, s[34:35]
	s_mov_b64 s[34:35], 0x8000
	v_lshl_add_u64 v[106:107], v[110:111], 0, s[34:35]
	v_pk_mul_f32 v[44:45], v[44:45], v[62:63] op_sel_hi:[1,0]
	v_pk_mul_f32 v[46:47], v[46:47], v[62:63] op_sel_hi:[1,0]
	v_pk_mul_f32 v[42:43], v[42:43], v[62:63] op_sel_hi:[1,0]
	v_pk_mul_f32 v[40:41], v[40:41], v[62:63] op_sel_hi:[1,0]
	v_pk_mul_f32 v[38:39], v[38:39], v[82:83] op_sel_hi:[1,0]
	v_pk_mul_f32 v[32:33], v[32:33], v[62:63] op_sel_hi:[1,0]
	v_pk_mul_f32 v[34:35], v[34:35], v[62:63] op_sel_hi:[1,0]
	v_pk_mul_f32 v[28:29], v[28:29], v[82:83] op_sel_hi:[1,0]
	v_pk_mul_f32 v[30:31], v[30:31], v[82:83] op_sel_hi:[1,0]
	v_pk_mul_f32 v[24:25], v[24:25], v[62:63] op_sel_hi:[1,0]
	v_pk_mul_f32 v[26:27], v[26:27], v[62:63] op_sel_hi:[1,0]
	v_pk_mul_f32 v[20:21], v[20:21], v[82:83] op_sel_hi:[1,0]
	v_pk_mul_f32 v[22:23], v[22:23], v[82:83] op_sel_hi:[1,0]
	v_pk_mul_f32 v[16:17], v[16:17], v[62:63] op_sel_hi:[1,0]
	v_pk_mul_f32 v[18:19], v[18:19], v[62:63] op_sel_hi:[1,0]
	v_pk_mul_f32 v[12:13], v[12:13], v[82:83] op_sel_hi:[1,0]
	v_pk_mul_f32 v[14:15], v[14:15], v[82:83] op_sel_hi:[1,0]
	v_pk_mul_f32 v[8:9], v[8:9], v[62:63] op_sel_hi:[1,0]
	v_pk_mul_f32 v[10:11], v[10:11], v[62:63] op_sel_hi:[1,0]
	v_pk_mul_f32 v[4:5], v[4:5], v[82:83] op_sel_hi:[1,0]
	v_pk_mul_f32 v[6:7], v[6:7], v[82:83] op_sel_hi:[1,0]
	v_pk_mul_f32 v[0:1], v[0:1], v[62:63] op_sel_hi:[1,0]
	v_pk_mul_f32 v[2:3], v[2:3], v[62:63] op_sel_hi:[1,0]
	s_waitcnt vmcnt(1)
	v_pk_add_f32 v[96:97], v[98:99], 1.0 op_sel_hi:[1,0]
	v_pk_add_f32 v[94:95], v[100:101], 1.0 op_sel_hi:[1,0]
	s_waitcnt vmcnt(0)
; __device__ __forceinline__ unsigned cvt_pk_bf16(float lo, float hi) { unsigned r; asm volatile("v_cvt_pk_bf16_f32 %0, %1, %2" : "=v"(r) : "v"(lo), "v"(hi)); return r; }
; __device__ __forceinline__ void norm_rows(const float* xl, const float* xc, const float* g, const float* modl, int sh_ofs, int sc_ofs, bf16_t* XN, int nrows, int gw, int NGW) {
;     ...
; #pragma unroll
;         for (int j = 0; j < 8; ++j) { const f32x4 gj = g4[64 * j];
;             const f32x4 ya = va[j] * rsa * gj * (sca[64 * j] + 1.0f) + sha[64 * j]; u32x2 w; w.x = cvt_pk_bf16(ya[0], ya[1]); w.y = cvt_pk_bf16(ya[2], ya[3]); oa[64 * j] = w;
;             const f32x4 yb = vb[j] * rsb * gj * (scb[64 * j] + 1.0f) + shb[64 * j]; u32x2 w2; w2.x = cvt_pk_bf16(yb[0], yb[1]); w2.y = cvt_pk_bf16(yb[2], yb[3]); ob[64 * j] = w2; }
	v_pk_fma_f32 v[56:57], v[96:97], v[56:57], v[102:103]
	v_pk_fma_f32 v[58:59], v[94:95], v[58:59], v[104:105]
	v_cvt_pk_bf16_f32 v56, v56, v57
	v_lshl_add_u64 v[102:103], v[108:109], 0, s[34:35]
	v_cvt_pk_bf16_f32 v57, v58, v59
	global_store_dwordx2 v[60:61], v[56:57], off
	v_lshl_add_u64 v[250:251], v[108:109], 0, s[42:43]
	v_lshl_add_u64 v[240:241], v[110:111], 0, s[42:43]
	global_load_dwordx4 v[116:119], v[64:65], off offset:1024
	global_load_dwordx4 v[120:123], v[102:103], off offset:1024
	global_load_dwordx4 v[124:127], v[250:251], off offset:1024
	global_load_dwordx4 v[128:131], v[106:107], off offset:1024
	global_load_dwordx4 v[132:135], v[240:241], off offset:1024
	global_load_dwordx4 v[136:139], v[64:65], off offset:2048
	global_load_dwordx4 v[140:143], v[102:103], off offset:2048
	global_load_dwordx4 v[144:147], v[250:251], off offset:2048
	global_load_dwordx4 v[148:151], v[106:107], off offset:2048
	global_load_dwordx4 v[152:155], v[240:241], off offset:2048
	global_load_dwordx4 v[156:159], v[64:65], off offset:3072
	global_load_dwordx4 v[160:163], v[102:103], off offset:3072
	global_load_dwordx4 v[164:167], v[250:251], off offset:3072
	global_load_dwordx4 v[168:171], v[106:107], off offset:3072
	global_load_dwordx4 v[172:175], v[240:241], off offset:3072
	global_load_dwordx4 v[176:179], v[68:69], off
	global_load_dwordx4 v[180:183], v[78:79], off
	global_load_dwordx4 v[184:187], v[80:81], off
	global_load_dwordx4 v[188:191], v[84:85], off
	global_load_dwordx4 v[192:195], v[86:87], off
	global_load_dwordx4 v[196:199], v[70:71], off
	global_load_dwordx4 v[200:203], v[78:79], off offset:1024
	global_load_dwordx4 v[204:207], v[80:81], off offset:1024
	global_load_dwordx4 v[210:213], v[84:85], off offset:1024
	global_load_dwordx4 v[218:221], v[86:87], off offset:1024
	global_load_dwordx4 v[222:225], v[72:73], off
	global_load_dwordx4 v[226:229], v[78:79], off offset:2048
	global_load_dwordx4 v[230:233], v[80:81], off offset:2048
	global_load_dwordx4 v[234:237], v[84:85], off offset:2048
	global_load_dwordx4 v[246:249], v[86:87], off offset:2048
	s_waitcnt vmcnt(0)
	s_nop 0
	v_lshl_add_u64 v[104:105], v[108:109], 0, s[42:43]
	s_nop 0
	s_nop 0
	v_readlane_b32 s34, v254, 45
	v_readlane_b32 s35, v254, 46
	s_nop 0
	v_pk_mul_f32 v[52:53], v[52:53], v[116:117]
	v_pk_mul_f32 v[54:55], v[54:55], v[118:119]
	s_nop 0
	v_pk_add_f32 v[94:95], v[120:121], 1.0 op_sel_hi:[1, 0]
	v_pk_add_f32 v[96:97], v[122:123], 1.0 op_sel_hi:[1, 0]
	s_nop 0
	v_pk_fma_f32 v[52:53], v[52:53], v[94:95], v[124:125]
	v_pk_fma_f32 v[54:55], v[54:55], v[96:97], v[126:127]
	v_cvt_pk_bf16_f32 v52, v52, v53
	v_lshl_add_u64 v[98:99], v[110:111], 0, s[42:43]
	v_cvt_pk_bf16_f32 v53, v54, v55
	global_store_dwordx2 v[76:77], v[52:53], off offset:512
	s_nop 0
	v_pk_mul_f32 v[44:45], v[116:117], v[44:45]
	s_nop 0
	v_pk_mul_f32 v[46:47], v[118:119], v[46:47]
	s_nop 0
	v_pk_add_f32 v[52:53], v[128:129], 1.0 op_sel_hi:[1, 0]
	v_pk_add_f32 v[54:55], v[130:131], 1.0 op_sel_hi:[1, 0]
	s_nop 0
	v_pk_fma_f32 v[44:45], v[44:45], v[52:53], v[132:133]
	v_pk_fma_f32 v[46:47], v[46:47], v[54:55], v[134:135]
	v_cvt_pk_bf16_f32 v44, v44, v45
	s_nop 0
	v_cvt_pk_bf16_f32 v45, v46, v47
	global_store_dwordx2 v[60:61], v[44:45], off offset:512
	s_nop 0
	s_nop 0
	s_nop 0
	s_nop 0
	s_nop 0
	v_pk_mul_f32 v[48:49], v[48:49], v[136:137]
	s_nop 0
	v_pk_add_f32 v[52:53], v[140:141], 1.0 op_sel_hi:[1, 0]
	v_pk_mul_f32 v[50:51], v[50:51], v[138:139]
	v_pk_add_f32 v[54:55], v[142:143], 1.0 op_sel_hi:[1, 0]
	s_nop 0
	v_pk_fma_f32 v[48:49], v[48:49], v[52:53], v[144:145]
	v_pk_fma_f32 v[50:51], v[50:51], v[54:55], v[146:147]
	v_cvt_pk_bf16_f32 v48, v48, v49
	v_pk_mul_f32 v[40:41], v[40:41], v[136:137]
	v_cvt_pk_bf16_f32 v49, v50, v51
	global_store_dwordx2 v[76:77], v[48:49], off offset:1024
	s_nop 0
	s_nop 0
	s_nop 0
	v_pk_mul_f32 v[42:43], v[42:43], v[138:139]
	s_nop 0
	v_pk_add_f32 v[46:47], v[148:149], 1.0 op_sel_hi:[1, 0]
	v_pk_add_f32 v[44:45], v[150:151], 1.0 op_sel_hi:[1, 0]
	s_nop 0
	v_pk_fma_f32 v[40:41], v[40:41], v[46:47], v[152:153]
	v_pk_fma_f32 v[42:43], v[42:43], v[44:45], v[154:155]
	v_cvt_pk_bf16_f32 v40, v40, v41
	s_nop 0
	v_cvt_pk_bf16_f32 v41, v42, v43
	global_store_dwordx2 v[60:61], v[40:41], off offset:1024
	s_nop 0
	s_nop 0
	s_nop 0
	s_nop 0
	s_nop 0
	v_pk_mul_f32 v[36:37], v[36:37], v[156:157]
	s_nop 0
	v_pk_add_f32 v[44:45], v[160:161], 1.0 op_sel_hi:[1, 0]
	v_pk_mul_f32 v[38:39], v[38:39], v[158:159]
	v_pk_add_f32 v[46:47], v[162:163], 1.0 op_sel_hi:[1, 0]
	s_nop 0
	v_pk_fma_f32 v[36:37], v[36:37], v[44:45], v[164:165]
	v_pk_fma_f32 v[38:39], v[38:39], v[46:47], v[166:167]
	v_cvt_pk_bf16_f32 v36, v36, v37
	v_pk_mul_f32 v[32:33], v[32:33], v[156:157]
	v_cvt_pk_bf16_f32 v37, v38, v39
; __device__ __forceinline__ unsigned cvt_pk_bf16(float lo, float hi) { unsigned r; asm volatile("v_cvt_pk_bf16_f32 %0, %1, %2" : "=v"(r) : "v"(lo), "v"(hi)); return r; }
; __device__ __forceinline__ void norm_rows(const float* xl, const float* xc, const float* g, const float* modl, int sh_ofs, int sc_ofs, bf16_t* XN, int nrows, int gw, int NGW) {
;     ...
; #pragma unroll
;         for (int j = 0; j < 8; ++j) { const f32x4 gj = g4[64 * j];
;             const f32x4 ya = va[j] * rsa * gj * (sca[64 * j] + 1.0f) + sha[64 * j]; u32x2 w; w.x = cvt_pk_bf16(ya[0], ya[1]); w.y = cvt_pk_bf16(ya[2], ya[3]); oa[64 * j] = w;
;             const f32x4 yb = vb[j] * rsb * gj * (scb[64 * j] + 1.0f) + shb[64 * j]; u32x2 w2; w2.x = cvt_pk_bf16(yb[0], yb[1]); w2.y = cvt_pk_bf16(yb[2], yb[3]); ob[64 * j] = w2; }
;     }
	global_store_dwordx2 v[76:77], v[36:37], off offset:1536
	s_nop 0
	s_nop 0
	s_nop 0
	v_pk_mul_f32 v[34:35], v[34:35], v[158:159]
	s_nop 0
	v_pk_add_f32 v[36:37], v[168:169], 1.0 op_sel_hi:[1, 0]
	v_pk_add_f32 v[38:39], v[170:171], 1.0 op_sel_hi:[1, 0]
	s_nop 0
	v_pk_fma_f32 v[32:33], v[32:33], v[36:37], v[172:173]
	v_pk_fma_f32 v[34:35], v[34:35], v[38:39], v[174:175]
	v_cvt_pk_bf16_f32 v32, v32, v33
	s_nop 0
	v_cvt_pk_bf16_f32 v33, v34, v35
	global_store_dwordx2 v[60:61], v[32:33], off offset:1536
	s_nop 0
	s_nop 0
	s_nop 0
	s_nop 0
	s_nop 0
	v_pk_mul_f32 v[28:29], v[28:29], v[176:177]
	s_nop 0
	v_pk_add_f32 v[36:37], v[180:181], 1.0 op_sel_hi:[1, 0]
	v_pk_mul_f32 v[30:31], v[30:31], v[178:179]
	v_pk_add_f32 v[38:39], v[182:183], 1.0 op_sel_hi:[1, 0]
	s_nop 0
	v_pk_fma_f32 v[28:29], v[28:29], v[36:37], v[184:185]
	v_pk_fma_f32 v[30:31], v[30:31], v[38:39], v[186:187]
	v_cvt_pk_bf16_f32 v28, v28, v29
	v_pk_mul_f32 v[24:25], v[24:25], v[176:177]
	v_cvt_pk_bf16_f32 v29, v30, v31
	global_store_dwordx2 v[76:77], v[28:29], off offset:2048
	s_nop 0
	s_nop 0
	s_nop 0
	v_pk_mul_f32 v[26:27], v[26:27], v[178:179]
	s_nop 0
	v_pk_add_f32 v[28:29], v[188:189], 1.0 op_sel_hi:[1, 0]
	v_pk_add_f32 v[30:31], v[190:191], 1.0 op_sel_hi:[1, 0]
	s_nop 0
	v_pk_fma_f32 v[24:25], v[24:25], v[28:29], v[192:193]
	v_pk_fma_f32 v[26:27], v[26:27], v[30:31], v[194:195]
	v_cvt_pk_bf16_f32 v24, v24, v25
	s_nop 0
	v_cvt_pk_bf16_f32 v25, v26, v27
	global_store_dwordx2 v[60:61], v[24:25], off offset:2048
	s_nop 0
	s_nop 0
	s_nop 0
	s_nop 0
	s_nop 0
	v_pk_mul_f32 v[20:21], v[20:21], v[196:197]
	s_nop 0
	v_pk_add_f32 v[28:29], v[200:201], 1.0 op_sel_hi:[1, 0]
	v_pk_mul_f32 v[22:23], v[22:23], v[198:199]
	v_pk_add_f32 v[30:31], v[202:203], 1.0 op_sel_hi:[1, 0]
	s_nop 0
	v_pk_fma_f32 v[20:21], v[20:21], v[28:29], v[204:205]
	v_pk_fma_f32 v[22:23], v[22:23], v[30:31], v[206:207]
	v_cvt_pk_bf16_f32 v20, v20, v21
	v_pk_mul_f32 v[16:17], v[16:17], v[196:197]
	v_cvt_pk_bf16_f32 v21, v22, v23
	global_store_dwordx2 v[76:77], v[20:21], off offset:2560
	s_nop 0
	s_nop 0
	s_nop 0
	v_pk_mul_f32 v[18:19], v[18:19], v[198:199]
	s_nop 0
	v_pk_add_f32 v[20:21], v[210:211], 1.0 op_sel_hi:[1, 0]
	v_pk_add_f32 v[22:23], v[212:213], 1.0 op_sel_hi:[1, 0]
	s_nop 0
	v_pk_fma_f32 v[16:17], v[16:17], v[20:21], v[218:219]
	v_pk_fma_f32 v[18:19], v[18:19], v[22:23], v[220:221]
	v_cvt_pk_bf16_f32 v16, v16, v17
	s_nop 0
	v_cvt_pk_bf16_f32 v17, v18, v19
	global_store_dwordx2 v[60:61], v[16:17], off offset:2560
	s_nop 0
	s_nop 0
	s_nop 0
	s_nop 0
	s_nop 0
	v_pk_mul_f32 v[12:13], v[12:13], v[222:223]
	s_nop 0
	v_pk_add_f32 v[20:21], v[226:227], 1.0 op_sel_hi:[1, 0]
	v_pk_mul_f32 v[14:15], v[14:15], v[224:225]
	v_pk_add_f32 v[22:23], v[228:229], 1.0 op_sel_hi:[1, 0]
	s_nop 0
	v_pk_fma_f32 v[12:13], v[12:13], v[20:21], v[230:231]
	v_pk_fma_f32 v[14:15], v[14:15], v[22:23], v[232:233]
	v_cvt_pk_bf16_f32 v12, v12, v13
	v_pk_mul_f32 v[8:9], v[8:9], v[222:223]
	v_cvt_pk_bf16_f32 v13, v14, v15
	global_store_dwordx2 v[76:77], v[12:13], off offset:3072
	s_nop 0
	s_nop 0
	s_nop 0
	v_pk_mul_f32 v[10:11], v[10:11], v[224:225]
	s_nop 0
	v_pk_add_f32 v[12:13], v[234:235], 1.0 op_sel_hi:[1, 0]
	v_pk_add_f32 v[14:15], v[236:237], 1.0 op_sel_hi:[1, 0]
	s_nop 0
	v_pk_fma_f32 v[8:9], v[8:9], v[12:13], v[246:247]
	v_pk_fma_f32 v[10:11], v[10:11], v[14:15], v[248:249]
	v_cvt_pk_bf16_f32 v8, v8, v9
	s_nop 0
	v_cvt_pk_bf16_f32 v9, v10, v11
	global_store_dwordx2 v[60:61], v[8:9], off offset:3072
	global_load_dwordx4 v[8:11], v[74:75], off
	s_nop 0
	global_load_dwordx4 v[12:15], v[78:79], off offset:3072
	global_load_dwordx4 v[16:19], v[80:81], off offset:3072
	s_waitcnt vmcnt(2)
	v_pk_mul_f32 v[4:5], v[4:5], v[8:9]
	s_waitcnt vmcnt(1)
	v_pk_add_f32 v[12:13], v[12:13], 1.0 op_sel_hi:[1, 0]
	v_pk_mul_f32 v[6:7], v[6:7], v[10:11]
	v_pk_add_f32 v[14:15], v[14:15], 1.0 op_sel_hi:[1, 0]
	s_waitcnt vmcnt(0)
	v_pk_fma_f32 v[4:5], v[4:5], v[12:13], v[16:17]
	v_pk_fma_f32 v[6:7], v[6:7], v[14:15], v[18:19]
	v_cvt_pk_bf16_f32 v4, v4, v5
	v_pk_mul_f32 v[0:1], v[0:1], v[8:9]
	v_cvt_pk_bf16_f32 v5, v6, v7
	global_store_dwordx2 v[76:77], v[4:5], off offset:3584
	global_load_dwordx4 v[4:7], v[84:85], off offset:3072
	s_nop 0
	global_load_dwordx4 v[12:15], v[86:87], off offset:3072
	v_pk_mul_f32 v[2:3], v[2:3], v[10:11]
	v_lshl_add_u64 v[76:77], v[76:77], 0, s[34:35]
	s_waitcnt vmcnt(1)
	v_pk_add_f32 v[4:5], v[4:5], 1.0 op_sel_hi:[1, 0]
	v_pk_add_f32 v[6:7], v[6:7], 1.0 op_sel_hi:[1, 0]
	s_waitcnt vmcnt(0)
	v_pk_fma_f32 v[0:1], v[0:1], v[4:5], v[12:13]
	v_pk_fma_f32 v[2:3], v[2:3], v[6:7], v[14:15]
	v_cvt_pk_bf16_f32 v0, v0, v1
	s_nop 0
	v_cvt_pk_bf16_f32 v1, v2, v3
	global_store_dwordx2 v[60:61], v[0:1], off offset:3584
	s_cbranch_scc0 .LBB0_161

; __device__ __forceinline__ void norm_rows(const float* xl, const float* xc, const float* g, const float* modl, int sh_ofs, int sc_ofs, bf16_t* XN, int nrows, int gw, int NGW) {
;     ...
;     for (int row = gw; row < nrows; row += 2 * NGW) {
;         const int rowb = (row + NGW < nrows) ? row + NGW : row;
;         const f32x4* s4a = (const f32x4*)(row < RL ? xl + (size_t)row * DM : xc + (size_t)(row - RL) * DM) + lane;
;         const f32x4* s4b = (const f32x4*)(rowb < RL ? xl + (size_t)rowb * DM : xc + (size_t)(rowb - RL) * DM) + lane;
;         const int mia = row < RL ? (row >> 11) : 16, mib = rowb < RL ? (rowb >> 11) : 16;
;         f32x4 va[8], vb[8]; float ssa = 0.f, ssb = 0.f;
; #pragma unroll
;         for (int j = 0; j < 8; ++j) { va[j] = __builtin_nontemporal_load(s4a + 64 * j); vb[j] = __builtin_nontemporal_load(s4b + 64 * j); }
; #pragma unroll
;         for (int j = 0; j < 8; ++j) { ssa += (va[j][0] * va[j][0] + va[j][1] * va[j][1]) + (va[j][2] * va[j][2] + va[j][3] * va[j][3]); ssb += (vb[j][0] * vb[j][0] + vb[j][1] * vb[j][1]) + (vb[j][2] * vb[j][2] + vb[j][3] * vb[j][3]); }
;         const float rsa = rsqrtf(wave_sum(ssa) * (1.0f / DM) + EPS), rsb = rsqrtf(wave_sum(ssb) * (1.0f / DM) + EPS);
.LBB0_501:
	s_add_i32 s18, s30, 0xffff8000
	s_mov_b64 s[28:29], s[42:43]
	s_add_u32 s28, s28, s0
	s_addc_u32 s29, s29, s1
	s_cmp_lt_i32 s30, 0x8000
	v_readlane_b32 s34, v254, 63
	s_cselect_b32 s29, s29, 0
	s_cselect_b32 s28, s28, s18
	v_readlane_b32 s35, v255, 0
	global_load_dwordx4 v[56:59], v208, s[16:17] nt
	global_load_dwordx4 v[48:51], v208, s[16:17] offset:1024 nt
	global_load_dwordx4 v[40:43], v208, s[16:17] offset:2048 nt
	s_cselect_b32 s18, s41, s35
	s_cselect_b32 s31, s40, s34
	s_lshl_b64 s[28:29], s[28:29], 13
	s_add_u32 s28, s31, s28
	s_addc_u32 s29, s18, s29
	v_lshl_add_u64 v[0:1], s[28:29], 0, v[208:209]
	global_load_dwordx4 v[60:63], v208, s[28:29] nt
	global_load_dwordx4 v[52:55], v208, s[28:29] offset:1024 nt
	global_load_dwordx4 v[44:47], v208, s[28:29] offset:2048 nt
	global_load_dwordx4 v[32:35], v208, s[28:29] offset:3072 nt
	v_add_co_u32_e32 v24, vcc, s96, v0
	v_readlane_b32 s28, v255, 3
	s_nop 0
	v_addc_co_u32_e32 v25, vcc, 0, v1, vcc
	global_load_dwordx4 v[20:23], v[24:25], off nt
	v_lshl_add_u64 v[0:1], s[16:17], 0, v[208:209]
	v_add_co_u32_e32 v0, vcc, s96, v0
	v_readlane_b32 s31, v255, 4
	s_nop 0
	v_addc_co_u32_e32 v1, vcc, 0, v1, vcc
	global_load_dwordx4 v[16:19], v[0:1], off nt
	global_load_dwordx4 v[28:31], v208, s[16:17] offset:3072 nt
	global_load_dwordx4 v[8:11], v[0:1], off offset:1024 nt
	global_load_dwordx4 v[4:7], v[0:1], off offset:2048 nt
	s_nop 0
	global_load_dwordx4 v[0:3], v[0:1], off offset:3072 nt
	s_min_i32 s16, s30, 0x8000
	global_load_dwordx4 v[12:15], v[24:25], off offset:1024 nt
	global_load_dwordx4 v[36:39], v[24:25], off offset:2048 nt
	s_nop 0
	global_load_dwordx4 v[24:27], v[24:25], off offset:3072 nt
	s_min_i32 s17, s14, 0x8000
	s_ashr_i32 s16, s16, 11
	s_ashr_i32 s18, s17, 11
	s_mul_hi_i32 s17, s16, 0xc000
	s_mul_i32 s16, s16, 0xc000
	s_add_u32 s16, s28, s16
	s_addc_u32 s17, s31, s17
	global_load_dwordx4 v[94:97], v208, s[16:17]
	s_mov_b32 s2, 0x3a000000
	s_mul_hi_i32 s29, s18, 0xc000
	s_mul_i32 s18, s18, 0xc000
	s_add_u32 s28, s28, s18
	s_addc_u32 s29, s31, s29
	s_lshl_b64 s[14:15], s[14:15], 12
	s_add_i32 s30, s30, s78
	s_add_u32 s0, s0, s78
	s_addc_u32 s1, s1, s79
	s_cmp_gt_i32 s30, 0x8fff
	s_waitcnt vmcnt(0)
	v_mov_b32_e32 v82, v57
	v_mov_b32_e32 v83, v49
	v_mov_b32_e32 v86, v59
	v_mov_b32_e32 v87, v51
	v_pk_mul_f32 v[98:99], v[42:43], v[42:43]
	v_pk_mul_f32 v[100:101], v[40:41], v[40:41]
	v_mov_b32_e32 v78, v56
	v_mov_b32_e32 v79, v48
	v_mov_b32_e32 v84, v58
	v_mov_b32_e32 v85, v50
	v_pk_mul_f32 v[82:83], v[82:83], v[82:83]
	v_pk_mul_f32 v[86:87], v[86:87], v[86:87]
	v_pk_mov_b32 v[102:103], v[100:101], v[98:99] op_sel:[1,0]
	v_mov_b32_e32 v101, v99
	v_pk_fma_f32 v[78:79], v[78:79], v[78:79], v[82:83]
	v_pk_fma_f32 v[82:83], v[84:85], v[84:85], v[86:87]
	v_pk_add_f32 v[84:85], v[102:103], v[100:101]
	v_mov_b32_e32 v86, v61
	v_mov_b32_e32 v87, v53
	v_mov_b32_e32 v100, v63
	v_mov_b32_e32 v101, v55
	v_pk_add_f32 v[78:79], v[78:79], v[82:83]
	v_mov_b32_e32 v82, v60
	v_mov_b32_e32 v83, v52
	v_mov_b32_e32 v98, v62
	v_mov_b32_e32 v99, v54
	v_pk_mul_f32 v[102:103], v[46:47], v[46:47]
	v_pk_mul_f32 v[104:105], v[44:45], v[44:45]
	v_pk_mul_f32 v[86:87], v[86:87], v[86:87]
	v_pk_mul_f32 v[100:101], v[100:101], v[100:101]
	v_pk_mov_b32 v[108:109], v[104:105], v[102:103] op_sel:[1,0]
	v_mov_b32_e32 v105, v103
	v_pk_fma_f32 v[82:83], v[82:83], v[82:83], v[86:87]
	v_pk_fma_f32 v[86:87], v[98:99], v[98:99], v[100:101]
	v_mul_f32_e32 v80, v33, v33
	v_pk_add_f32 v[98:99], v[108:109], v[104:105]
	v_pk_add_f32 v[82:83], v[82:83], v[86:87]
	v_pk_fma_f32 v[102:103], v[32:33], v[32:33], v[80:81] op_sel_hi:[1,1,0]
	v_mul_f32_e32 v80, v20, v20
	v_mul_f32_e32 v93, v21, v21
	v_pk_add_f32 v[86:87], v[98:99], v[98:99] op_sel:[0,1] op_sel_hi:[1,0]
	v_pk_add_f32 v[82:83], v[82:83], v[82:83] op_sel:[0,1] op_sel_hi:[1,0]
	v_mul_f32_e32 v106, v35, v35
	v_mov_b32_e32 v87, v93
	v_mov_b32_e32 v83, v80
	v_mul_f32_e32 v101, v23, v23
	v_pk_add_f32 v[82:83], v[82:83], v[86:87]
	v_pk_fma_f32 v[86:87], v[34:35], v[34:35], v[106:107] op_sel_hi:[1,1,0]
	v_mul_f32_e32 v103, v22, v22
	v_mov_b32_e32 v87, v101
	v_pk_add_f32 v[86:87], v[102:103], v[86:87]
	v_mul_f32_e32 v80, v16, v16
	v_pk_add_f32 v[82:83], v[82:83], v[86:87]
	v_mul_f32_e32 v86, v17, v17
	v_pk_add_f32 v[78:79], v[78:79], v[78:79] op_sel:[0,1] op_sel_hi:[1,0]
	v_pk_add_f32 v[84:85], v[84:85], v[84:85] op_sel:[0,1] op_sel_hi:[1,0]
	v_mov_b32_e32 v79, v80
	v_mov_b32_e32 v85, v86
	v_mul_f32_e32 v80, v29, v29
	v_mul_f32_e32 v87, v18, v18
	v_pk_add_f32 v[78:79], v[78:79], v[84:85]
	v_pk_fma_f32 v[84:85], v[28:29], v[28:29], v[80:81] op_sel_hi:[1,1,0]
	v_mul_f32_e32 v80, v31, v31
	v_mul_f32_e32 v93, v19, v19
	v_mov_b32_e32 v85, v87
	v_pk_fma_f32 v[86:87], v[30:31], v[30:31], v[80:81] op_sel_hi:[1,1,0]
	v_mul_f32_e32 v80, v24, v24
	v_mov_b32_e32 v87, v93
	v_pk_add_f32 v[84:85], v[84:85], v[86:87]
	v_pk_mul_f32 v[86:87], v[12:13], v[12:13]
	v_pk_add_f32 v[84:85], v[78:79], v[84:85]
	v_pk_mul_f32 v[78:79], v[14:15], v[14:15]
	v_pk_add_f32 v[82:83], v[82:83], v[82:83] op_sel:[0,1] op_sel_hi:[1,0]
	v_pk_mov_b32 v[98:99], v[86:87], v[78:79] op_sel:[1,0]
	v_mov_b32_e32 v87, v79
	v_pk_add_f32 v[78:79], v[98:99], v[86:87]
	v_pk_mul_f32 v[86:87], v[10:11], v[10:11]
	v_pk_mul_f32 v[98:99], v[8:9], v[8:9]
	v_pk_add_f32 v[78:79], v[78:79], v[78:79] op_sel:[0,1] op_sel_hi:[1,0]
	v_pk_mov_b32 v[100:101], v[98:99], v[86:87] op_sel:[1,0]
	v_mul_f32_e32 v86, v25, v25
	v_mov_b32_e32 v83, v80
	v_mov_b32_e32 v79, v86
	v_mul_f32_e32 v80, v37, v37
	v_mov_b32_e32 v99, v87
	v_mul_f32_e32 v87, v26, v26
	v_pk_add_f32 v[78:79], v[82:83], v[78:79]
	v_pk_fma_f32 v[82:83], v[36:37], v[36:37], v[80:81] op_sel_hi:[1,1,0]
	v_mul_f32_e32 v80, v39, v39
	v_mul_f32_e32 v93, v27, v27
	v_mov_b32_e32 v83, v87
	v_pk_fma_f32 v[86:87], v[38:39], v[38:39], v[80:81] op_sel_hi:[1,1,0]
	v_pk_add_f32 v[106:107], v[100:101], v[98:99]
	v_mov_b32_e32 v87, v93
	v_pk_add_f32 v[82:83], v[82:83], v[86:87]
	v_lshl_add_u64 v[86:87], s[16:17], 0, v[208:209]
	v_pk_add_f32 v[82:83], v[78:79], v[82:83]
	v_add_co_u32_e32 v78, vcc, s9, v86
	global_load_dwordx4 v[98:101], v[64:65], off
	s_nop 0
	v_addc_co_u32_e32 v79, vcc, 0, v87, vcc
	global_load_dwordx4 v[102:105], v[78:79], off offset:-4096
	v_mul_f32_e32 v80, v0, v0
	v_mul_f32_e32 v93, v1, v1
	v_pk_add_f32 v[84:85], v[84:85], v[84:85] op_sel:[0,1] op_sel_hi:[1,0]
	v_pk_add_f32 v[106:107], v[106:107], v[106:107] op_sel:[0,1] op_sel_hi:[1,0]
	v_mov_b32_e32 v85, v80
	v_mov_b32_e32 v107, v93
	v_mul_f32_e32 v80, v5, v5
	v_mul_f32_e32 v108, v2, v2
	v_pk_add_f32 v[84:85], v[84:85], v[106:107]
	v_pk_fma_f32 v[106:107], v[4:5], v[4:5], v[80:81] op_sel_hi:[1,1,0]
	v_mul_f32_e32 v80, v7, v7
	v_mul_f32_e32 v110, v3, v3
	v_mov_b32_e32 v107, v108
	v_pk_fma_f32 v[108:109], v[6:7], v[6:7], v[80:81] op_sel_hi:[1,1,0]
	s_waitcnt vmcnt(0)
; __device__ __forceinline__ unsigned cvt_pk_bf16(float lo, float hi) { unsigned r; asm volatile("v_cvt_pk_bf16_f32 %0, %1, %2" : "=v"(r) : "v"(lo), "v"(hi)); return r; }
; __device__ __forceinline__ void norm_rows(const float* xl, const float* xc, const float* g, const float* modl, int sh_ofs, int sc_ofs, bf16_t* XN, int nrows, int gw, int NGW) {
;     ...
;         const float rsa = rsqrtf(wave_sum(ssa) * (1.0f / DM) + EPS), rsb = rsqrtf(wave_sum(ssb) * (1.0f / DM) + EPS);
;         const f32x4* g4 = (const f32x4*)g + lane;
;         const f32x4* sca = (const f32x4*)(modl + (size_t)mia * 12288 + sc_ofs) + lane; const f32x4* sha = (const f32x4*)(modl + (size_t)mia * 12288 + sh_ofs) + lane;
;         const f32x4* scb = (const f32x4*)(modl + (size_t)mib * 12288 + sc_ofs) + lane; const f32x4* shb = (const f32x4*)(modl + (size_t)mib * 12288 + sh_ofs) + lane;
;         u32x2* oa = (u32x2*)(XN + (size_t)row * DM) + lane; u32x2* ob = (u32x2*)(XN + (size_t)rowb * DM) + lane;
; #pragma unroll
;         for (int j = 0; j < 8; ++j) { const f32x4 gj = g4[64 * j];
;             const f32x4 ya = va[j] * rsa * gj * (sca[64 * j] + 1.0f) + sha[64 * j]; u32x2 w; w.x = cvt_pk_bf16(ya[0], ya[1]); w.y = cvt_pk_bf16(ya[2], ya[3]); oa[64 * j] = w;
;             const f32x4 yb = vb[j] * rsb * gj * (scb[64 * j] + 1.0f) + shb[64 * j]; u32x2 w2; w2.x = cvt_pk_bf16(yb[0], yb[1]); w2.y = cvt_pk_bf16(yb[2], yb[3]); ob[64 * j] = w2; }
	v_pk_add_f32 v[102:103], v[102:103], 1.0 op_sel_hi:[1,0]
	v_mov_b32_e32 v109, v110
	v_pk_add_f32 v[106:107], v[106:107], v[108:109]
	s_nop 0
	v_pk_add_f32 v[84:85], v[84:85], v[106:107]
	v_mov_b32_e32 v107, v82
	v_mov_b32_e32 v106, v84
	v_mov_b32_e32 v82, v85
	v_pk_add_f32 v[82:83], v[106:107], v[82:83]
	ds_bpermute_b32 v85, v81, v83
	ds_bpermute_b32 v84, v81, v82
	s_waitcnt lgkmcnt(0)
	v_pk_add_f32 v[82:83], v[82:83], v[84:85]
	ds_bpermute_b32 v85, v88, v83
	ds_bpermute_b32 v84, v88, v82
	s_waitcnt lgkmcnt(0)
	v_pk_add_f32 v[82:83], v[82:83], v[84:85]
	ds_bpermute_b32 v85, v89, v83
	ds_bpermute_b32 v84, v89, v82
	s_waitcnt lgkmcnt(0)
	v_pk_add_f32 v[82:83], v[82:83], v[84:85]
	ds_bpermute_b32 v85, v90, v83
	ds_bpermute_b32 v84, v90, v82
	s_waitcnt lgkmcnt(0)
	v_pk_add_f32 v[82:83], v[82:83], v[84:85]
	ds_bpermute_b32 v85, v91, v83
	ds_bpermute_b32 v84, v91, v82
	s_waitcnt lgkmcnt(0)
	v_pk_add_f32 v[82:83], v[82:83], v[84:85]
	ds_bpermute_b32 v85, v92, v83
	ds_bpermute_b32 v84, v92, v82
	s_waitcnt lgkmcnt(0)
	v_pk_add_f32 v[82:83], v[82:83], v[84:85]
	s_nop 0
	v_pk_fma_f32 v[106:107], v[82:83], s[2:3], v[238:239] op_sel_hi:[1,0,0]
	s_mov_b32 s2, 0x800000
	v_mul_f32_e32 v80, 0x4b800000, v107
	v_cmp_gt_f32_e32 vcc, s2, v107
	v_lshl_add_u64 v[84:85], s[28:29], 0, v[208:209]
	s_nop 0
	v_cndmask_b32_e32 v80, v107, v80, vcc
	v_rsq_f32_e32 v80, v80
	s_nop 0
	v_mul_f32_e32 v82, 0x45800000, v80
	v_cndmask_b32_e32 v80, v80, v82, vcc
	v_pk_mul_f32 v[62:63], v[62:63], v[80:81] op_sel_hi:[1,0]
	v_pk_mul_f32 v[60:61], v[60:61], v[80:81] op_sel_hi:[1,0]
	v_pk_mul_f32 v[62:63], v[100:101], v[62:63]
	v_pk_mul_f32 v[60:61], v[98:99], v[60:61]
	v_pk_add_f32 v[82:83], v[104:105], 1.0 op_sel_hi:[1,0]
	v_pk_fma_f32 v[60:61], v[102:103], v[60:61], v[94:95]
	v_pk_fma_f32 v[62:63], v[82:83], v[62:63], v[96:97]
	v_add_co_u32_e32 v82, vcc, s9, v84
	v_cvt_pk_bf16_f32 v60, v60, v61
	v_cvt_pk_bf16_f32 v61, v62, v63
	global_store_dwordx2 v[76:77], v[60:61], off
	s_nop 0
	v_addc_co_u32_e32 v83, vcc, 0, v85, vcc
	global_load_dwordx4 v[94:97], v[82:83], off offset:-4096
	global_load_dwordx4 v[102:105], v208, s[28:29]
	v_mul_f32_e32 v60, 0x4b800000, v106
	v_cmp_gt_f32_e32 vcc, s2, v106
	v_pk_mul_f32 v[52:53], v[52:53], v[80:81] op_sel_hi:[1,0]
	v_pk_mul_f32 v[54:55], v[54:55], v[80:81] op_sel_hi:[1,0]
	v_cndmask_b32_e32 v60, v106, v60, vcc
	v_rsq_f32_e32 v62, v60
	v_lshl_add_u64 v[60:61], v[66:67], 0, s[14:15]
	s_mov_b64 s[14:15], 0x2000
	v_pk_mul_f32 v[44:45], v[44:45], v[80:81] op_sel_hi:[1,0]
	v_mul_f32_e32 v63, 0x45800000, v62
	v_cndmask_b32_e32 v62, v62, v63, vcc
	v_pk_mul_f32 v[56:57], v[56:57], v[62:63] op_sel_hi:[1,0]
	v_pk_mul_f32 v[58:59], v[58:59], v[62:63] op_sel_hi:[1,0]
	v_pk_mul_f32 v[56:57], v[98:99], v[56:57]
	v_pk_mul_f32 v[58:59], v[100:101], v[58:59]
	v_pk_mul_f32 v[48:49], v[48:49], v[62:63] op_sel_hi:[1,0]
	v_pk_mul_f32 v[50:51], v[50:51], v[62:63] op_sel_hi:[1,0]
	v_pk_mul_f32 v[46:47], v[46:47], v[80:81] op_sel_hi:[1,0]
	v_pk_mul_f32 v[40:41], v[40:41], v[62:63] op_sel_hi:[1,0]
	v_pk_mul_f32 v[42:43], v[42:43], v[62:63] op_sel_hi:[1,0]
	v_pk_mul_f32 v[32:33], v[32:33], v[80:81] op_sel_hi:[1,0]
	v_pk_mul_f32 v[34:35], v[34:35], v[80:81] op_sel_hi:[1,0]
	v_pk_mul_f32 v[28:29], v[28:29], v[62:63] op_sel_hi:[1,0]
	v_pk_mul_f32 v[30:31], v[30:31], v[62:63] op_sel_hi:[1,0]
	v_pk_mul_f32 v[20:21], v[20:21], v[80:81] op_sel_hi:[1,0]
	v_pk_mul_f32 v[22:23], v[22:23], v[80:81] op_sel_hi:[1,0]
	v_pk_mul_f32 v[16:17], v[16:17], v[62:63] op_sel_hi:[1,0]
	v_pk_mul_f32 v[18:19], v[18:19], v[62:63] op_sel_hi:[1,0]
	v_pk_mul_f32 v[12:13], v[12:13], v[80:81] op_sel_hi:[1,0]
	v_pk_mul_f32 v[14:15], v[14:15], v[80:81] op_sel_hi:[1,0]
	v_pk_mul_f32 v[8:9], v[8:9], v[62:63] op_sel_hi:[1,0]
	v_pk_mul_f32 v[10:11], v[10:11], v[62:63] op_sel_hi:[1,0]
	v_pk_mul_f32 v[6:7], v[6:7], v[62:63] op_sel_hi:[1,0]
	v_pk_mul_f32 v[4:5], v[4:5], v[62:63] op_sel_hi:[1,0]
	v_pk_mul_f32 v[2:3], v[2:3], v[62:63] op_sel_hi:[1,0]
	v_pk_mul_f32 v[0:1], v[0:1], v[62:63] op_sel_hi:[1,0]
	s_waitcnt vmcnt(1)
	v_pk_add_f32 v[94:95], v[94:95], 1.0 op_sel_hi:[1,0]
	v_pk_add_f32 v[96:97], v[96:97], 1.0 op_sel_hi:[1,0]
	s_waitcnt vmcnt(0)
	v_pk_fma_f32 v[56:57], v[94:95], v[56:57], v[102:103]
	v_pk_fma_f32 v[58:59], v[96:97], v[58:59], v[104:105]
	v_cvt_pk_bf16_f32 v56, v56, v57
	v_lshl_add_u64 v[102:103], v[86:87], 0, s[14:15]
	v_cvt_pk_bf16_f32 v57, v58, v59
	global_store_dwordx2 v[60:61], v[56:57], off
	v_lshl_add_u64 v[246:247], v[84:85], 0, s[14:15]
	v_add_co_u32_e32 v248, vcc, s96, v86
	s_nop 1
	v_addc_co_u32_e32 v249, vcc, 0, v87, vcc
	v_add_co_u32_e32 v250, vcc, s96, v84
	s_nop 1
	v_addc_co_u32_e32 v251, vcc, 0, v85, vcc
	global_load_dwordx4 v[112:115], v[64:65], off offset:1024
	global_load_dwordx4 v[116:119], v[102:103], off offset:1024
	global_load_dwordx4 v[120:123], v208, s[16:17] offset:1024
	global_load_dwordx4 v[124:127], v[246:247], off offset:1024
	global_load_dwordx4 v[128:131], v208, s[28:29] offset:1024
	global_load_dwordx4 v[132:135], v[64:65], off offset:2048
	global_load_dwordx4 v[136:139], v[102:103], off offset:2048
	global_load_dwordx4 v[140:143], v208, s[16:17] offset:2048
	global_load_dwordx4 v[144:147], v[246:247], off offset:2048
	global_load_dwordx4 v[148:151], v208, s[28:29] offset:2048
	global_load_dwordx4 v[152:155], v[64:65], off offset:3072
	global_load_dwordx4 v[156:159], v[102:103], off offset:3072
	global_load_dwordx4 v[160:163], v208, s[16:17] offset:3072
	global_load_dwordx4 v[164:167], v[246:247], off offset:3072
	global_load_dwordx4 v[168:171], v208, s[28:29] offset:3072
	global_load_dwordx4 v[172:175], v[68:69], off
	global_load_dwordx4 v[176:179], v[78:79], off
	global_load_dwordx4 v[180:183], v[248:249], off
	global_load_dwordx4 v[184:187], v[82:83], off
	global_load_dwordx4 v[188:191], v[250:251], off
	global_load_dwordx4 v[192:195], v[70:71], off
	global_load_dwordx4 v[196:199], v[78:79], off offset:1024
	global_load_dwordx4 v[200:203], v[248:249], off offset:1024
	global_load_dwordx4 v[204:207], v[82:83], off offset:1024
	global_load_dwordx4 v[210:213], v[250:251], off offset:1024
	global_load_dwordx4 v[218:221], v[72:73], off
	global_load_dwordx4 v[222:225], v[78:79], off offset:2048
	global_load_dwordx4 v[226:229], v[248:249], off offset:2048
	global_load_dwordx4 v[230:233], v[82:83], off offset:2048
	global_load_dwordx4 v[234:237], v[250:251], off offset:2048
	s_waitcnt vmcnt(0)
; __device__ __forceinline__ unsigned cvt_pk_bf16(float lo, float hi) { unsigned r; asm volatile("v_cvt_pk_bf16_f32 %0, %1, %2" : "=v"(r) : "v"(lo), "v"(hi)); return r; }
; __device__ __forceinline__ void norm_rows(const float* xl, const float* xc, const float* g, const float* modl, int sh_ofs, int sc_ofs, bf16_t* XN, int nrows, int gw, int NGW) {
;     ...
;         for (int j = 0; j < 8; ++j) { const f32x4 gj = g4[64 * j];
;             const f32x4 ya = va[j] * rsa * gj * (sca[64 * j] + 1.0f) + sha[64 * j]; u32x2 w; w.x = cvt_pk_bf16(ya[0], ya[1]); w.y = cvt_pk_bf16(ya[2], ya[3]); oa[64 * j] = w;
;             const f32x4 yb = vb[j] * rsb * gj * (scb[64 * j] + 1.0f) + shb[64 * j]; u32x2 w2; w2.x = cvt_pk_bf16(yb[0], yb[1]); w2.y = cvt_pk_bf16(yb[2], yb[3]); ob[64 * j] = w2; }
	s_nop 0
	s_nop 0
	s_nop 0
	s_nop 0
	v_lshl_add_u64 v[104:105], v[84:85], 0, s[14:15]
	v_readlane_b32 s14, v254, 45
	v_readlane_b32 s15, v254, 46
	s_nop 0
	v_pk_mul_f32 v[52:53], v[52:53], v[112:113]
	s_nop 0
	v_pk_add_f32 v[94:95], v[116:117], 1.0 op_sel_hi:[1, 0]
	v_pk_mul_f32 v[54:55], v[54:55], v[114:115]
	v_pk_add_f32 v[96:97], v[118:119], 1.0 op_sel_hi:[1, 0]
	s_nop 0
	v_pk_fma_f32 v[52:53], v[52:53], v[94:95], v[120:121]
	v_pk_fma_f32 v[54:55], v[54:55], v[96:97], v[122:123]
	v_cvt_pk_bf16_f32 v52, v52, v53
	v_pk_mul_f32 v[48:49], v[112:113], v[48:49]
	v_cvt_pk_bf16_f32 v53, v54, v55
	global_store_dwordx2 v[76:77], v[52:53], off offset:512
	s_nop 0
	s_nop 0
	s_nop 0
	v_pk_mul_f32 v[50:51], v[114:115], v[50:51]
	s_nop 0
	v_pk_add_f32 v[52:53], v[124:125], 1.0 op_sel_hi:[1, 0]
	v_pk_add_f32 v[54:55], v[126:127], 1.0 op_sel_hi:[1, 0]
	s_nop 0
	v_pk_fma_f32 v[48:49], v[48:49], v[52:53], v[128:129]
	v_pk_fma_f32 v[50:51], v[50:51], v[54:55], v[130:131]
	v_cvt_pk_bf16_f32 v48, v48, v49
	s_nop 0
	v_cvt_pk_bf16_f32 v49, v50, v51
	global_store_dwordx2 v[60:61], v[48:49], off offset:512
	s_nop 0
	s_nop 0
	s_nop 0
	s_nop 0
	s_nop 0
	v_pk_mul_f32 v[44:45], v[44:45], v[132:133]
	s_nop 0
	v_pk_add_f32 v[52:53], v[136:137], 1.0 op_sel_hi:[1, 0]
	v_pk_mul_f32 v[46:47], v[46:47], v[134:135]
	v_pk_add_f32 v[54:55], v[138:139], 1.0 op_sel_hi:[1, 0]
	s_nop 0
	v_pk_fma_f32 v[44:45], v[44:45], v[52:53], v[140:141]
	v_pk_fma_f32 v[46:47], v[46:47], v[54:55], v[142:143]
	v_cvt_pk_bf16_f32 v44, v44, v45
	v_pk_mul_f32 v[40:41], v[40:41], v[132:133]
	v_cvt_pk_bf16_f32 v45, v46, v47
	global_store_dwordx2 v[76:77], v[44:45], off offset:1024
	s_nop 0
	s_nop 0
	s_nop 0
	v_pk_mul_f32 v[42:43], v[42:43], v[134:135]
	s_nop 0
	v_pk_add_f32 v[44:45], v[144:145], 1.0 op_sel_hi:[1, 0]
	v_pk_add_f32 v[46:47], v[146:147], 1.0 op_sel_hi:[1, 0]
	s_nop 0
	v_pk_fma_f32 v[40:41], v[40:41], v[44:45], v[148:149]
	v_pk_fma_f32 v[42:43], v[42:43], v[46:47], v[150:151]
	v_cvt_pk_bf16_f32 v40, v40, v41
	s_nop 0
	v_cvt_pk_bf16_f32 v41, v42, v43
	global_store_dwordx2 v[60:61], v[40:41], off offset:1024
	s_nop 0
	s_nop 0
	s_nop 0
	s_nop 0
	s_nop 0
	v_pk_mul_f32 v[32:33], v[32:33], v[152:153]
	s_nop 0
	v_pk_add_f32 v[44:45], v[156:157], 1.0 op_sel_hi:[1, 0]
	v_pk_mul_f32 v[34:35], v[34:35], v[154:155]
	v_pk_add_f32 v[46:47], v[158:159], 1.0 op_sel_hi:[1, 0]
	s_nop 0
	v_pk_fma_f32 v[32:33], v[32:33], v[44:45], v[160:161]
	v_pk_fma_f32 v[34:35], v[34:35], v[46:47], v[162:163]
	v_cvt_pk_bf16_f32 v32, v32, v33
	v_pk_mul_f32 v[28:29], v[28:29], v[152:153]
	v_cvt_pk_bf16_f32 v33, v34, v35
	global_store_dwordx2 v[76:77], v[32:33], off offset:1536
	s_nop 0
	s_nop 0
	s_nop 0
	v_pk_mul_f32 v[30:31], v[30:31], v[154:155]
	s_nop 0
	v_pk_add_f32 v[32:33], v[164:165], 1.0 op_sel_hi:[1, 0]
	v_pk_add_f32 v[34:35], v[166:167], 1.0 op_sel_hi:[1, 0]
	s_nop 0
	v_pk_fma_f32 v[28:29], v[28:29], v[32:33], v[168:169]
	v_pk_fma_f32 v[30:31], v[30:31], v[34:35], v[170:171]
	v_cvt_pk_bf16_f32 v28, v28, v29
	v_add_co_u32_e32 v44, vcc, s96, v86
	v_cvt_pk_bf16_f32 v29, v30, v31
	global_store_dwordx2 v[60:61], v[28:29], off offset:1536
	s_nop 0
	s_nop 0
	s_nop 0
	v_addc_co_u32_e32 v45, vcc, 0, v87, vcc
	s_nop 0
	s_nop 0
	v_pk_mul_f32 v[20:21], v[20:21], v[172:173]
	s_nop 0
	v_pk_add_f32 v[32:33], v[176:177], 1.0 op_sel_hi:[1, 0]
	v_pk_mul_f32 v[22:23], v[22:23], v[174:175]
	v_pk_add_f32 v[34:35], v[178:179], 1.0 op_sel_hi:[1, 0]
	s_nop 0
	v_pk_fma_f32 v[20:21], v[20:21], v[32:33], v[180:181]
	v_pk_fma_f32 v[22:23], v[22:23], v[34:35], v[182:183]
	v_cvt_pk_bf16_f32 v20, v20, v21
	v_add_co_u32_e32 v40, vcc, s96, v84
	v_cvt_pk_bf16_f32 v21, v22, v23
	global_store_dwordx2 v[76:77], v[20:21], off offset:2048
	s_nop 0
	v_addc_co_u32_e32 v41, vcc, 0, v85, vcc
	s_nop 0
	v_pk_mul_f32 v[16:17], v[16:17], v[172:173]
	v_pk_mul_f32 v[18:19], v[18:19], v[174:175]
	s_nop 0
	v_pk_add_f32 v[20:21], v[184:185], 1.0 op_sel_hi:[1, 0]
	v_pk_add_f32 v[22:23], v[186:187], 1.0 op_sel_hi:[1, 0]
	s_nop 0
	v_pk_fma_f32 v[16:17], v[16:17], v[20:21], v[188:189]
	v_pk_fma_f32 v[18:19], v[18:19], v[22:23], v[190:191]
	v_cvt_pk_bf16_f32 v16, v16, v17
	s_nop 0
	v_cvt_pk_bf16_f32 v17, v18, v19
	global_store_dwordx2 v[60:61], v[16:17], off offset:2048
	s_nop 0
	s_nop 0
	s_nop 0
	s_nop 0
	s_nop 0
	v_pk_mul_f32 v[12:13], v[12:13], v[192:193]
	s_nop 0
	v_pk_add_f32 v[20:21], v[196:197], 1.0 op_sel_hi:[1, 0]
	v_pk_mul_f32 v[14:15], v[14:15], v[194:195]
	v_pk_add_f32 v[22:23], v[198:199], 1.0 op_sel_hi:[1, 0]
	s_nop 0
	v_pk_fma_f32 v[12:13], v[12:13], v[20:21], v[200:201]
	v_pk_fma_f32 v[14:15], v[14:15], v[22:23], v[202:203]
	v_cvt_pk_bf16_f32 v12, v12, v13
	v_pk_mul_f32 v[8:9], v[8:9], v[192:193]
	v_cvt_pk_bf16_f32 v13, v14, v15
	global_store_dwordx2 v[76:77], v[12:13], off offset:2560
	s_nop 0
	s_nop 0
	s_nop 0
	v_pk_mul_f32 v[10:11], v[10:11], v[194:195]
	s_nop 0
	v_pk_add_f32 v[12:13], v[204:205], 1.0 op_sel_hi:[1, 0]
	v_pk_add_f32 v[14:15], v[206:207], 1.0 op_sel_hi:[1, 0]
	s_nop 0
	v_pk_fma_f32 v[8:9], v[8:9], v[12:13], v[210:211]
	v_pk_fma_f32 v[10:11], v[10:11], v[14:15], v[212:213]
	v_cvt_pk_bf16_f32 v8, v8, v9
	v_pk_mul_f32 v[22:23], v[36:37], v[80:81] op_sel_hi:[1, 0]
	v_cvt_pk_bf16_f32 v9, v10, v11
	global_store_dwordx2 v[60:61], v[8:9], off offset:2560
	s_nop 0
	s_nop 0
	s_nop 0
	s_nop 0
	v_pk_mul_f32 v[20:21], v[38:39], v[80:81] op_sel_hi:[1, 0]
	s_nop 0
	v_pk_mul_f32 v[22:23], v[22:23], v[218:219]
	s_nop 0
	v_pk_add_f32 v[12:13], v[222:223], 1.0 op_sel_hi:[1, 0]
	v_pk_mul_f32 v[20:21], v[20:21], v[220:221]
	v_pk_add_f32 v[14:15], v[224:225], 1.0 op_sel_hi:[1, 0]
	s_nop 0
	v_pk_fma_f32 v[12:13], v[22:23], v[12:13], v[226:227]
	v_pk_fma_f32 v[14:15], v[20:21], v[14:15], v[228:229]
	v_cvt_pk_bf16_f32 v12, v12, v13
	v_pk_mul_f32 v[4:5], v[4:5], v[218:219]
	v_cvt_pk_bf16_f32 v13, v14, v15
	global_store_dwordx2 v[76:77], v[12:13], off offset:3072
	s_nop 0
	s_nop 0
	s_nop 0
	v_pk_mul_f32 v[6:7], v[6:7], v[220:221]
	s_nop 0
	v_pk_add_f32 v[10:11], v[230:231], 1.0 op_sel_hi:[1, 0]
	v_pk_add_f32 v[8:9], v[232:233], 1.0 op_sel_hi:[1, 0]
	s_nop 0
	v_pk_fma_f32 v[4:5], v[4:5], v[10:11], v[234:235]
	v_pk_fma_f32 v[6:7], v[6:7], v[8:9], v[236:237]
	v_cvt_pk_bf16_f32 v4, v4, v5
	v_pk_mul_f32 v[18:19], v[24:25], v[80:81] op_sel_hi:[1, 0]
	v_cvt_pk_bf16_f32 v5, v6, v7
	global_store_dwordx2 v[60:61], v[4:5], off offset:3072
	global_load_dwordx4 v[4:7], v[74:75], off
	s_nop 0
	global_load_dwordx4 v[8:11], v[78:79], off offset:3072
	global_load_dwordx4 v[12:15], v[44:45], off offset:3072
	v_pk_mul_f32 v[16:17], v[26:27], v[80:81] op_sel_hi:[1, 0]
	s_waitcnt vmcnt(2)
; __device__ __forceinline__ unsigned cvt_pk_bf16(float lo, float hi) { unsigned r; asm volatile("v_cvt_pk_bf16_f32 %0, %1, %2" : "=v"(r) : "v"(lo), "v"(hi)); return r; }
; __device__ __forceinline__ void norm_rows(const float* xl, const float* xc, const float* g, const float* modl, int sh_ofs, int sc_ofs, bf16_t* XN, int nrows, int gw, int NGW) {
;     ...
;         for (int j = 0; j < 8; ++j) { const f32x4 gj = g4[64 * j];
;             const f32x4 ya = va[j] * rsa * gj * (sca[64 * j] + 1.0f) + sha[64 * j]; u32x2 w; w.x = cvt_pk_bf16(ya[0], ya[1]); w.y = cvt_pk_bf16(ya[2], ya[3]); oa[64 * j] = w;
;             const f32x4 yb = vb[j] * rsb * gj * (scb[64 * j] + 1.0f) + shb[64 * j]; u32x2 w2; w2.x = cvt_pk_bf16(yb[0], yb[1]); w2.y = cvt_pk_bf16(yb[2], yb[3]); ob[64 * j] = w2; }
	v_pk_mul_f32 v[18:19], v[18:19], v[4:5]
	s_waitcnt vmcnt(1)
	v_pk_add_f32 v[8:9], v[8:9], 1.0 op_sel_hi:[1, 0]
	v_pk_mul_f32 v[16:17], v[16:17], v[6:7]
	v_pk_add_f32 v[10:11], v[10:11], 1.0 op_sel_hi:[1, 0]
	s_waitcnt vmcnt(0)
	v_pk_fma_f32 v[8:9], v[18:19], v[8:9], v[12:13]
	v_pk_fma_f32 v[10:11], v[16:17], v[10:11], v[14:15]
	v_cvt_pk_bf16_f32 v8, v8, v9
	v_pk_mul_f32 v[0:1], v[0:1], v[4:5]
	v_cvt_pk_bf16_f32 v9, v10, v11
	global_store_dwordx2 v[76:77], v[8:9], off offset:3584
	global_load_dwordx4 v[8:11], v[82:83], off offset:3072
	s_nop 0
	global_load_dwordx4 v[12:15], v[40:41], off offset:3072
	v_pk_mul_f32 v[2:3], v[2:3], v[6:7]
	v_lshl_add_u64 v[76:77], v[76:77], 0, s[14:15]
	s_waitcnt vmcnt(1)
	v_pk_add_f32 v[6:7], v[8:9], 1.0 op_sel_hi:[1, 0]
	v_pk_add_f32 v[4:5], v[10:11], 1.0 op_sel_hi:[1, 0]
	s_waitcnt vmcnt(0)
	v_pk_fma_f32 v[0:1], v[0:1], v[6:7], v[12:13]
	v_pk_fma_f32 v[2:3], v[2:3], v[4:5], v[14:15]
	v_cvt_pk_bf16_f32 v0, v0, v1
	s_nop 0
	v_cvt_pk_bf16_f32 v1, v2, v3
	global_store_dwordx2 v[60:61], v[0:1], off offset:3584
	s_cbranch_scc1 .LBB0_506
